# P6 epilogue: second batch of residual x loads of each half prefetched alongside the first batch (spare VGPRs), ladders recounted
# speedup vs baseline: 1.0022x; 1.0022x over previous
; DI unsigned pk_bf16(float lo, float hi) { f32x2v v = {lo, hi}; bf16x2v b = __builtin_convertvector(v, bf16x2v); return __builtin_bit_cast(unsigned, b); }
; DI int tid_() { int t = threadIdx.x; asm volatile("" : "+v"(t)); return t; }
; DI void lds_sync() { wait_lgkm0(); bar_(); }
; DI void phase6(const Params& p, char* smem) {
;     ...
;     const int tc_ = tid_();
;     const int ch = tc_ & 63, r0 = tc_ >> 6;
;     const float4 g = *(const float4*)(p.mod + (tokTile >> 3) * 6144 + 2048 + nt * 256 + ch * 4);
; #pragma unroll
;     for (int tn = 0; tn < 2; ++tn) {
;       const size_t obase = ((size_t)tokTile * 256 + tn * 32) * DM + nt * 256 + ch * 4;
; #pragma unroll
;       for (int tm = 0; tm < 4; ++tm) {
;         char* d = smem + (wn * 32 + r) * 1040 + (wm * 128 + tm * 32 + 4 * hh) * 4;
; #pragma unroll
;         for (int q = 0; q < 4; ++q) *(float4*)(d + 32 * q) = make_float4(acc[tm][tn][4 * q], acc[tm][tn][4 * q + 1], acc[tm][tn][4 * q + 2], acc[tm][tn][4 * q + 3]);
;       }
;       lds_sync();
; #pragma unroll
;       for (int hb = 0; hb < 2; ++hb) {
;         float4 xv[8];
; #pragma unroll
;         for (int i = 0; i < 8; ++i) {
;           const int row = r0 + 8 * (hb * 8 + i);
;           xv[i] = *(const float4*)(p.x + obase + (size_t)((row >> 5) * 64 + (row & 31)) * DM);
;         }
; #pragma unroll
;         for (int i = 0; i < 8; ++i) {
;           const int row = r0 + 8 * (hb * 8 + i);
;           const float4 a = *(const float4*)(smem + row * 1040 + ch * 16);
;           uint2 ob; ob.x = pk_bf16(xv[i].x + g.x * a.x, xv[i].y + g.y * a.y); ob.y = pk_bf16(xv[i].z + g.z * a.z, xv[i].w + g.w * a.w);
;           *(uint2*)(p.x1b + obase + (size_t)((row >> 5) * 64 + (row & 31)) * DM) = ob;
;         }
;       }
.Lp6_cont:
	s_mov_b64 s[50:51], 0x80000
	s_setprio 0
	s_lshr_b32 s4, s44, 3
	s_mulk_i32 s4, 0x6000
	s_add_u32 s4, s14, s4
	v_mov_b32_e32 v128, v220
	s_addc_u32 s5, s15, 0
	s_lshl_b32 s7, s43, 8
	s_lshl_b32 s8, s43, 10
	s_waitcnt lgkmcnt(0)
	s_barrier
	s_add_u32 s4, s4, s8
	v_and_b32_e32 v129, 63, v128
	s_addc_u32 s5, s5, 0
	v_lshlrev_b32_e32 v184, 4, v129
	v_ashrrev_i32_e32 v132, 6, v128
	v_lshl_add_u64 v[130:131], s[4:5], 0, v[184:185]
	s_or_b32 s4, s6, s7
	v_lshl_or_b32 v136, v129, 2, s4
	v_mad_u64_u32 v[128:129], s[4:5], v132, s34, v[184:185]
	v_and_b32_e32 v137, 31, v132
	v_lshlrev_b32_e32 v129, 1, v132
	s_waitcnt vmcnt(0)
	ds_write_b128 v202, v[112:115]
	ds_write_b128 v202, v[116:119] offset:32
	ds_write_b128 v202, v[120:123] offset:64
	ds_write_b128 v202, v[124:127] offset:96
	ds_write_b128 v202, v[96:99] offset:128
	ds_write_b128 v202, v[100:103] offset:160
	ds_write_b128 v202, v[104:107] offset:192
	ds_write_b128 v202, v[108:111] offset:224
	ds_write_b128 v202, v[80:83] offset:256
	ds_write_b128 v202, v[84:87] offset:288
	ds_write_b128 v202, v[88:91] offset:320
	ds_write_b128 v202, v[92:95] offset:352
	ds_write_b128 v202, v[64:67] offset:384
	ds_write_b128 v202, v[68:71] offset:416
	ds_write_b128 v202, v[72:75] offset:448
	ds_write_b128 v202, v[76:79] offset:480
	v_and_or_b32 v126, v129, s41, v137
	v_lshlrev_b32_e32 v184, 2, v136
	v_ashrrev_i32_e32 v127, 31, v126
	v_lshl_add_u64 v[116:117], s[16:17], 0, v[184:185]
	v_lshlrev_b64 v[68:69], 12, v[126:127]
	v_add_co_u32_e32 v64, vcc, s38, v130
	v_add_u32_e32 v133, 8, v132
	v_lshl_add_u64 v[70:71], v[116:117], 0, v[68:69]
	v_addc_co_u32_e32 v65, vcc, 0, v131, vcc
	global_load_dwordx4 v[64:67], v[64:65], off
	s_waitcnt lgkmcnt(0)
	s_barrier
	v_lshl_add_u64 v[240:241], v[70:71], 0, s[50:51]
	global_load_dwordx4 v[192:195], v[240:241], off
	global_load_dwordx4 v[84:87], v[70:71], off
	v_and_b32_e32 v150, 31, v133
	v_lshlrev_b32_e32 v70, 1, v133
	v_and_or_b32 v130, v70, s41, v150
	v_ashrrev_i32_e32 v131, 31, v130
	v_lshlrev_b64 v[70:71], 12, v[130:131]
	v_lshl_add_u64 v[72:73], v[116:117], 0, v[70:71]
	v_bitop3_b32 v151, v132, 16, 31 bitop3:0x6c
	v_lshl_add_u64 v[240:241], v[72:73], 0, s[50:51]
	global_load_dwordx4 v[196:199], v[240:241], off
	global_load_dwordx4 v[88:91], v[72:73], off
	v_add_u32_e32 v72, 32, v129
	v_add_u32_e32 v76, 24, v132
	v_and_or_b32 v132, v72, s41, v151
	v_ashrrev_i32_e32 v133, 31, v132
	v_lshlrev_b64 v[72:73], 12, v[132:133]
	v_lshl_add_u64 v[74:75], v[116:117], 0, v[72:73]
	v_and_b32_e32 v154, 31, v76
	v_lshl_add_u64 v[240:241], v[74:75], 0, s[50:51]
	global_load_dwordx4 v[204:207], v[240:241], off
	global_load_dwordx4 v[92:95], v[74:75], off
	v_lshlrev_b32_e32 v74, 1, v76
	v_and_or_b32 v138, v74, s41, v154
	v_ashrrev_i32_e32 v139, 31, v138
	v_lshlrev_b64 v[74:75], 12, v[138:139]
	v_lshl_add_u64 v[76:77], v[116:117], 0, v[74:75]
	v_lshl_add_u64 v[240:241], v[76:77], 0, s[50:51]
	global_load_dwordx4 v[208:211], v[240:241], off
	global_load_dwordx4 v[96:99], v[76:77], off
	v_add_u32_e32 v76, 64, v129
	v_and_or_b32 v140, v76, s41, v137
	v_ashrrev_i32_e32 v141, 31, v140
	v_lshlrev_b64 v[76:77], 12, v[140:141]
	v_lshl_add_u64 v[78:79], v[116:117], 0, v[76:77]
	v_lshl_add_u64 v[240:241], v[78:79], 0, s[50:51]
	global_load_dwordx4 v[212:215], v[240:241], off
	global_load_dwordx4 v[100:103], v[78:79], off
	v_add_u32_e32 v78, 0x50, v129
	v_and_or_b32 v142, v78, s41, v150
	v_ashrrev_i32_e32 v143, 31, v142
	v_lshlrev_b64 v[78:79], 12, v[142:143]
	v_lshl_add_u64 v[80:81], v[116:117], 0, v[78:79]
	v_lshl_add_u64 v[240:241], v[80:81], 0, s[50:51]
	global_load_dwordx4 v[216:219], v[240:241], off
	global_load_dwordx4 v[104:107], v[80:81], off
	v_add_u32_e32 v80, 0x60, v129
	v_and_or_b32 v144, v80, s41, v151
	v_ashrrev_i32_e32 v145, 31, v144
	v_lshlrev_b64 v[80:81], 12, v[144:145]
	v_lshl_add_u64 v[82:83], v[116:117], 0, v[80:81]
	v_lshl_add_u64 v[240:241], v[82:83], 0, s[50:51]
	global_load_dwordx4 v[222:225], v[240:241], off
	global_load_dwordx4 v[108:111], v[82:83], off
	v_add_u32_e32 v82, 0x70, v129
	v_and_or_b32 v146, v82, s41, v154
	v_ashrrev_i32_e32 v147, 31, v146
	v_lshlrev_b64 v[82:83], 12, v[146:147]
	v_lshl_add_u64 v[112:113], v[116:117], 0, v[82:83]
	v_lshl_add_u64 v[240:241], v[112:113], 0, s[50:51]
	global_load_dwordx4 v[226:229], v[240:241], off
	global_load_dwordx4 v[112:115], v[112:113], off
	ds_read_b128 v[118:121], v128
	ds_read_b128 v[122:125], v128 offset:8320
	v_lshlrev_b32_e32 v184, 1, v136
	v_lshl_add_u64 v[134:135], s[18:19], 0, v[184:185]
	v_add_u32_e32 v186, 0x6180, v128
	v_add_u32_e32 v187, 0x8200, v128
	v_add_u32_e32 v188, 0xa280, v128
	v_add_u32_e32 v189, 0xc300, v128
	v_add_u32_e32 v190, 0xe380, v128
	s_add_i32 s42, s42, s95
	s_add_i32 s31, s31, s95
	s_cmpk_lt_u32 s42, 0x80
	s_waitcnt vmcnt(14) lgkmcnt(1)
	v_pk_fma_f32 v[84:85], v[64:65], v[118:119], v[84:85]
	s_nop 0
	v_cvt_pk_bf16_f32 v148, v84, v85
	v_pk_fma_f32 v[84:85], v[66:67], v[120:121], v[86:87]
	ds_read_b128 v[118:121], v128 offset:24960
	v_cvt_pk_bf16_f32 v149, v84, v85
	v_lshlrev_b64 v[84:85], 11, v[126:127]
	v_lshl_add_u64 v[126:127], v[134:135], 0, v[84:85]
	s_waitcnt vmcnt(12) lgkmcnt(1)
	v_pk_fma_f32 v[86:87], v[64:65], v[122:123], v[88:89]
	s_nop 0
	v_cvt_pk_bf16_f32 v122, v86, v87
	v_pk_fma_f32 v[86:87], v[66:67], v[124:125], v[90:91]
	ds_read_b128 v[88:91], v128 offset:16640
	v_cvt_pk_bf16_f32 v123, v86, v87
	v_lshlrev_b64 v[86:87], 11, v[130:131]
	v_lshl_add_u64 v[124:125], v[134:135], 0, v[86:87]
	s_waitcnt vmcnt(10) lgkmcnt(0)
	v_pk_fma_f32 v[88:89], v[64:65], v[88:89], v[92:93]
	s_nop 0
	v_cvt_pk_bf16_f32 v130, v88, v89
	v_pk_fma_f32 v[88:89], v[66:67], v[90:91], v[94:95]
	ds_read_b128 v[92:95], v128 offset:33280
	v_cvt_pk_bf16_f32 v131, v88, v89
	v_lshlrev_b64 v[88:89], 11, v[132:133]
	s_waitcnt vmcnt(8)
; DI unsigned pk_bf16(float lo, float hi) { f32x2v v = {lo, hi}; bf16x2v b = __builtin_convertvector(v, bf16x2v); return __builtin_bit_cast(unsigned, b); }
; DI void phase6(const Params& p, char* smem) {
;     ...
; #pragma unroll
;       for (int hb = 0; hb < 2; ++hb) {
;         float4 xv[8];
; #pragma unroll
;         for (int i = 0; i < 8; ++i) {
;           const int row = r0 + 8 * (hb * 8 + i);
;           xv[i] = *(const float4*)(p.x + obase + (size_t)((row >> 5) * 64 + (row & 31)) * DM);
;         }
; #pragma unroll
;         for (int i = 0; i < 8; ++i) {
;           const int row = r0 + 8 * (hb * 8 + i);
;           const float4 a = *(const float4*)(smem + row * 1040 + ch * 16);
;           uint2 ob; ob.x = pk_bf16(xv[i].x + g.x * a.x, xv[i].y + g.y * a.y); ob.y = pk_bf16(xv[i].z + g.z * a.z, xv[i].w + g.w * a.w);
;           *(uint2*)(p.x1b + obase + (size_t)((row >> 5) * 64 + (row & 31)) * DM) = ob;
;         }
;       }
	v_pk_fma_f32 v[90:91], v[64:65], v[118:119], v[96:97]
	v_lshl_add_u64 v[132:133], v[134:135], 0, v[88:89]
	v_cvt_pk_bf16_f32 v118, v90, v91
	v_pk_fma_f32 v[90:91], v[66:67], v[120:121], v[98:99]
	ds_read_b128 v[96:99], v128 offset:41600
	v_cvt_pk_bf16_f32 v119, v90, v91
	s_waitcnt vmcnt(6) lgkmcnt(1)
	v_pk_fma_f32 v[92:93], v[64:65], v[92:93], v[100:101]
	v_lshlrev_b64 v[90:91], 11, v[138:139]
	v_cvt_pk_bf16_f32 v138, v92, v93
	v_pk_fma_f32 v[92:93], v[66:67], v[94:95], v[102:103]
	ds_read_b128 v[100:103], v128 offset:58240
	v_cvt_pk_bf16_f32 v139, v92, v93
	s_waitcnt vmcnt(4) lgkmcnt(1)
	v_pk_fma_f32 v[94:95], v[64:65], v[96:97], v[104:105]
	v_lshlrev_b64 v[92:93], 11, v[140:141]
	v_cvt_pk_bf16_f32 v104, v94, v95
	v_pk_fma_f32 v[94:95], v[66:67], v[98:99], v[106:107]
	ds_read_b128 v[96:99], v128 offset:49920
	v_cvt_pk_bf16_f32 v105, v94, v95
	v_lshlrev_b64 v[94:95], 11, v[142:143]
	v_lshl_add_u64 v[120:121], v[134:135], 0, v[90:91]
	v_lshl_add_u64 v[140:141], v[134:135], 0, v[92:93]
	s_waitcnt vmcnt(2) lgkmcnt(0)
	v_pk_fma_f32 v[96:97], v[64:65], v[96:97], v[108:109]
	v_lshl_add_u64 v[106:107], v[134:135], 0, v[94:95]
	v_cvt_pk_bf16_f32 v108, v96, v97
	v_pk_fma_f32 v[96:97], v[66:67], v[98:99], v[110:111]
	s_waitcnt vmcnt(0)
	v_pk_fma_f32 v[100:101], v[64:65], v[100:101], v[112:113]
	v_cvt_pk_bf16_f32 v109, v96, v97
	v_lshlrev_b64 v[96:97], 11, v[144:145]
	v_lshl_add_u64 v[98:99], v[134:135], 0, v[96:97]
	global_store_dwordx2 v[126:127], v[148:149], off
	global_store_dwordx2 v[124:125], v[122:123], off
	global_store_dwordx2 v[132:133], v[130:131], off
	global_store_dwordx2 v[120:121], v[118:119], off
	global_store_dwordx2 v[140:141], v[138:139], off
	global_store_dwordx2 v[106:107], v[104:105], off
	global_store_dwordx2 v[98:99], v[108:109], off
	v_pk_fma_f32 v[98:99], v[66:67], v[102:103], v[114:115]
	v_cvt_pk_bf16_f32 v100, v100, v101
	v_cvt_pk_bf16_f32 v101, v98, v99
	v_lshlrev_b64 v[98:99], 11, v[146:147]
	v_lshl_add_u64 v[102:103], v[134:135], 0, v[98:99]
	global_store_dwordx2 v[102:103], v[100:101], off
	v_add_u32_e32 v100, 0x80, v129
	v_and_or_b32 v126, v100, s41, v137
	v_ashrrev_i32_e32 v127, 31, v126
	v_lshlrev_b64 v[100:101], 12, v[126:127]
	v_lshl_add_u64 v[102:103], v[116:117], 0, v[100:101]
	v_mov_b64_e32 v[118:119], v[192:193]
	v_mov_b64_e32 v[120:121], v[194:195]
	v_add_u32_e32 v102, 0x90, v129
	v_and_or_b32 v162, v102, s41, v150
	v_ashrrev_i32_e32 v163, 31, v162
	v_lshlrev_b64 v[102:103], 12, v[162:163]
	v_lshl_add_u64 v[104:105], v[116:117], 0, v[102:103]
	v_mov_b64_e32 v[122:123], v[196:197]
	v_mov_b64_e32 v[124:125], v[198:199]
	v_add_u32_e32 v104, 0xa0, v129
	v_and_or_b32 v164, v104, s41, v151
	v_ashrrev_i32_e32 v165, 31, v164
	v_lshlrev_b64 v[104:105], 12, v[164:165]
	v_lshl_add_u64 v[106:107], v[116:117], 0, v[104:105]
	v_mov_b64_e32 v[130:131], v[204:205]
	v_mov_b64_e32 v[132:133], v[206:207]
	v_add_u32_e32 v106, 0xb0, v129
	v_and_or_b32 v166, v106, s41, v154
	v_ashrrev_i32_e32 v167, 31, v166
	v_lshlrev_b64 v[106:107], 12, v[166:167]
	v_lshl_add_u64 v[108:109], v[116:117], 0, v[106:107]
	v_mov_b64_e32 v[138:139], v[208:209]
	v_mov_b64_e32 v[140:141], v[210:211]
	v_add_u32_e32 v108, 0xc0, v129
	v_and_or_b32 v168, v108, s41, v137
	v_ashrrev_i32_e32 v169, 31, v168
	v_lshlrev_b64 v[108:109], 12, v[168:169]
	v_lshl_add_u64 v[110:111], v[116:117], 0, v[108:109]
	v_mov_b64_e32 v[142:143], v[212:213]
	v_mov_b64_e32 v[144:145], v[214:215]
	v_add_u32_e32 v110, 0xd0, v129
	v_and_or_b32 v170, v110, s41, v150
	v_ashrrev_i32_e32 v171, 31, v170
	v_lshlrev_b64 v[110:111], 12, v[170:171]
	v_lshl_add_u64 v[112:113], v[116:117], 0, v[110:111]
	v_mov_b64_e32 v[146:147], v[216:217]
	v_mov_b64_e32 v[148:149], v[218:219]
	v_add_u32_e32 v112, 0xe0, v129
	v_and_or_b32 v172, v112, s41, v151
	v_ashrrev_i32_e32 v173, 31, v172
	v_lshlrev_b64 v[112:113], 12, v[172:173]
	v_lshl_add_u64 v[114:115], v[116:117], 0, v[112:113]
	v_mov_b64_e32 v[150:151], v[222:223]
	v_mov_b64_e32 v[152:153], v[224:225]
	v_add_u32_e32 v114, 0xf0, v129
	v_and_or_b32 v174, v114, s41, v154
	v_ashrrev_i32_e32 v175, 31, v174
	v_lshlrev_b64 v[114:115], 12, v[174:175]
	v_lshl_add_u64 v[116:117], v[116:117], 0, v[114:115]
	v_mov_b64_e32 v[154:155], v[226:227]
	v_mov_b64_e32 v[156:157], v[228:229]
	v_add_u32_e32 v129, 0x10400, v128
	ds_read_b128 v[158:161], v129
	v_add_u32_e32 v137, 0x4100, v128
	v_add_u32_e32 v191, 0xe380, v137
	s_waitcnt lgkmcnt(0)
	v_pk_fma_f32 v[116:117], v[64:65], v[158:159], v[118:119]
	s_nop 0
	v_cvt_pk_bf16_f32 v176, v116, v117
	v_pk_fma_f32 v[116:117], v[66:67], v[160:161], v[120:121]
	ds_read_b128 v[118:121], v137 offset:58240
	ds_read_b128 v[158:161], v186 offset:58240
	v_cvt_pk_bf16_f32 v177, v116, v117
	v_lshlrev_b64 v[116:117], 11, v[126:127]
	v_lshl_add_u64 v[178:179], v[134:135], 0, v[116:117]
	s_waitcnt lgkmcnt(1)
	v_pk_fma_f32 v[118:119], v[64:65], v[118:119], v[122:123]
	s_nop 0
	v_cvt_pk_bf16_f32 v180, v118, v119
	v_pk_fma_f32 v[118:119], v[66:67], v[120:121], v[124:125]
	s_waitcnt lgkmcnt(0)
	v_pk_fma_f32 v[120:121], v[64:65], v[158:159], v[130:131]
	ds_read_b128 v[122:125], v187 offset:58240
	v_cvt_pk_bf16_f32 v158, v120, v121
	v_pk_fma_f32 v[120:121], v[66:67], v[160:161], v[132:133]
	ds_read_b128 v[130:133], v188 offset:58240
	v_cvt_pk_bf16_f32 v159, v120, v121
	s_waitcnt lgkmcnt(1)
	v_pk_fma_f32 v[122:123], v[64:65], v[122:123], v[138:139]
	v_lshlrev_b64 v[120:121], 11, v[164:165]
	v_cvt_pk_bf16_f32 v164, v122, v123
	v_pk_fma_f32 v[122:123], v[66:67], v[124:125], v[140:141]
	ds_read_b128 v[138:141], v190 offset:58240
	v_cvt_pk_bf16_f32 v181, v118, v119
	s_waitcnt lgkmcnt(1)
; DI unsigned pk_bf16(float lo, float hi) { f32x2v v = {lo, hi}; bf16x2v b = __builtin_convertvector(v, bf16x2v); return __builtin_bit_cast(unsigned, b); }
; DI void lds_sync() { wait_lgkm0(); bar_(); }
; DI void phase6(const Params& p, char* smem) {
;     ...
; #pragma unroll
;     for (int tn = 0; tn < 2; ++tn) {
;       const size_t obase = ((size_t)tokTile * 256 + tn * 32) * DM + nt * 256 + ch * 4;
; #pragma unroll
;       for (int tm = 0; tm < 4; ++tm) {
;         char* d = smem + (wn * 32 + r) * 1040 + (wm * 128 + tm * 32 + 4 * hh) * 4;
; #pragma unroll
;         for (int q = 0; q < 4; ++q) *(float4*)(d + 32 * q) = make_float4(acc[tm][tn][4 * q], acc[tm][tn][4 * q + 1], acc[tm][tn][4 * q + 2], acc[tm][tn][4 * q + 3]);
;       }
;       lds_sync();
; #pragma unroll
;       for (int hb = 0; hb < 2; ++hb) {
;         float4 xv[8];
; #pragma unroll
;         for (int i = 0; i < 8; ++i) {
;           const int row = r0 + 8 * (hb * 8 + i);
;           xv[i] = *(const float4*)(p.x + obase + (size_t)((row >> 5) * 64 + (row & 31)) * DM);
;         }
; #pragma unroll
;         for (int i = 0; i < 8; ++i) {
;           const int row = r0 + 8 * (hb * 8 + i);
;           const float4 a = *(const float4*)(smem + row * 1040 + ch * 16);
;           uint2 ob; ob.x = pk_bf16(xv[i].x + g.x * a.x, xv[i].y + g.y * a.y); ob.y = pk_bf16(xv[i].z + g.z * a.z, xv[i].w + g.w * a.w);
;           *(uint2*)(p.x1b + obase + (size_t)((row >> 5) * 64 + (row & 31)) * DM) = ob;
;         }
;       }
	v_pk_fma_f32 v[124:125], v[64:65], v[130:131], v[142:143]
	v_lshlrev_b64 v[118:119], 11, v[162:163]
	v_cvt_pk_bf16_f32 v182, v124, v125
	v_pk_fma_f32 v[124:125], v[66:67], v[132:133], v[144:145]
	ds_read_b128 v[130:133], v189 offset:58240
	ds_read_b128 v[142:145], v191 offset:49920
	v_cvt_pk_bf16_f32 v165, v122, v123
	v_lshlrev_b64 v[122:123], 11, v[166:167]
	v_cvt_pk_bf16_f32 v183, v124, v125
	s_waitcnt lgkmcnt(1)
	v_pk_fma_f32 v[126:127], v[64:65], v[130:131], v[146:147]
	v_lshlrev_b64 v[124:125], 11, v[168:169]
	v_cvt_pk_bf16_f32 v146, v126, v127
	v_pk_fma_f32 v[126:127], v[66:67], v[132:133], v[148:149]
	v_pk_fma_f32 v[130:131], v[64:65], v[138:139], v[150:151]
	v_cvt_pk_bf16_f32 v147, v126, v127
	v_lshlrev_b64 v[126:127], 11, v[170:171]
	v_cvt_pk_bf16_f32 v138, v130, v131
	v_pk_fma_f32 v[130:131], v[66:67], v[140:141], v[152:153]
	v_lshl_add_u64 v[132:133], v[134:135], 0, v[126:127]
	v_cvt_pk_bf16_f32 v139, v130, v131
	v_lshlrev_b64 v[130:131], 11, v[172:173]
	v_lshl_add_u64 v[162:163], v[134:135], 0, v[118:119]
	v_lshl_add_u64 v[160:161], v[134:135], 0, v[120:121]
	v_lshl_add_u64 v[166:167], v[134:135], 0, v[122:123]
	v_lshl_add_u64 v[168:169], v[134:135], 0, v[124:125]
	v_lshl_add_u64 v[140:141], v[134:135], 0, v[130:131]
	s_waitcnt lgkmcnt(0)
	v_pk_fma_f32 v[142:143], v[64:65], v[142:143], v[154:155]
	global_store_dwordx2 v[178:179], v[176:177], off
	global_store_dwordx2 v[162:163], v[180:181], off
	global_store_dwordx2 v[160:161], v[158:159], off
	global_store_dwordx2 v[166:167], v[164:165], off
	global_store_dwordx2 v[168:169], v[182:183], off
	global_store_dwordx2 v[132:133], v[146:147], off
	global_store_dwordx2 v[140:141], v[138:139], off
	v_pk_fma_f32 v[132:133], v[66:67], v[144:145], v[156:157]
	v_cvt_pk_bf16_f32 v142, v142, v143
	v_cvt_pk_bf16_f32 v143, v132, v133
	v_lshlrev_b64 v[132:133], 11, v[174:175]
	v_lshl_add_u64 v[134:135], v[134:135], 0, v[132:133]
	global_store_dwordx2 v[134:135], v[142:143], off
	v_or_b32_e32 v134, 0x8000, v136
	v_lshlrev_b32_e32 v184, 2, v134
	s_waitcnt lgkmcnt(0)
	s_barrier
	ds_write_b128 v202, v[48:51]
	ds_write_b128 v202, v[52:55] offset:32
	ds_write_b128 v202, v[56:59] offset:64
	ds_write_b128 v202, v[60:63] offset:96
	ds_write_b128 v202, v[32:35] offset:128
	ds_write_b128 v202, v[36:39] offset:160
	ds_write_b128 v202, v[40:43] offset:192
	ds_write_b128 v202, v[44:47] offset:224
	ds_write_b128 v202, v[16:19] offset:256
	ds_write_b128 v202, v[20:23] offset:288
	ds_write_b128 v202, v[24:27] offset:320
	ds_write_b128 v202, v[28:31] offset:352
	ds_write_b128 v202, v[0:3] offset:384
	ds_write_b128 v202, v[4:7] offset:416
	ds_write_b128 v202, v[8:11] offset:448
	ds_write_b128 v202, v[12:15] offset:480
	v_lshl_add_u64 v[0:1], s[16:17], 0, v[184:185]
	v_lshl_add_u64 v[2:3], v[0:1], 0, v[68:69]
	s_waitcnt lgkmcnt(0)
	s_barrier
	v_lshl_add_u64 v[240:241], v[2:3], 0, s[50:51]
	global_load_dwordx4 v[192:195], v[240:241], off
	global_load_dwordx4 v[2:5], v[2:3], off
	v_lshl_add_u64 v[6:7], v[0:1], 0, v[70:71]
	v_lshl_add_u64 v[240:241], v[6:7], 0, s[50:51]
	global_load_dwordx4 v[196:199], v[240:241], off
	global_load_dwordx4 v[6:9], v[6:7], off
	v_lshl_add_u64 v[10:11], v[0:1], 0, v[72:73]
	v_lshl_add_u64 v[240:241], v[10:11], 0, s[50:51]
	global_load_dwordx4 v[204:207], v[240:241], off
	global_load_dwordx4 v[10:13], v[10:11], off
	v_lshl_add_u64 v[14:15], v[0:1], 0, v[74:75]
	v_lshl_add_u64 v[240:241], v[14:15], 0, s[50:51]
	global_load_dwordx4 v[208:211], v[240:241], off
	global_load_dwordx4 v[14:17], v[14:15], off
	v_lshl_add_u64 v[18:19], v[0:1], 0, v[76:77]
	v_lshl_add_u64 v[240:241], v[18:19], 0, s[50:51]
	global_load_dwordx4 v[212:215], v[240:241], off
	global_load_dwordx4 v[18:21], v[18:19], off
	v_lshl_add_u64 v[22:23], v[0:1], 0, v[78:79]
	v_lshl_add_u64 v[240:241], v[22:23], 0, s[50:51]
	global_load_dwordx4 v[216:219], v[240:241], off
	global_load_dwordx4 v[22:25], v[22:23], off
	v_lshl_add_u64 v[26:27], v[0:1], 0, v[80:81]
	v_lshl_add_u64 v[240:241], v[26:27], 0, s[50:51]
	global_load_dwordx4 v[222:225], v[240:241], off
	global_load_dwordx4 v[26:29], v[26:27], off
	v_lshl_add_u64 v[30:31], v[0:1], 0, v[82:83]
	v_lshl_add_u64 v[240:241], v[30:31], 0, s[50:51]
	global_load_dwordx4 v[226:229], v[240:241], off
	global_load_dwordx4 v[30:33], v[30:31], off
	ds_read_b128 v[34:37], v128
	ds_read_b128 v[38:41], v128 offset:8320
	v_lshlrev_b32_e32 v184, 1, v134
	v_lshl_add_u64 v[42:43], s[18:19], 0, v[184:185]
	s_waitcnt vmcnt(14) lgkmcnt(1)
	v_pk_fma_f32 v[2:3], v[64:65], v[34:35], v[2:3]
	s_nop 0
	v_cvt_pk_bf16_f32 v34, v2, v3
	v_pk_fma_f32 v[2:3], v[66:67], v[36:37], v[4:5]
	v_lshl_add_u64 v[36:37], v[42:43], 0, v[84:85]
	v_cvt_pk_bf16_f32 v35, v2, v3
	s_waitcnt vmcnt(12) lgkmcnt(0)
	v_pk_fma_f32 v[2:3], v[64:65], v[38:39], v[6:7]
	v_pk_fma_f32 v[6:7], v[66:67], v[40:41], v[8:9]
	v_cvt_pk_bf16_f32 v38, v2, v3
	ds_read_b128 v[2:5], v128 offset:16640
	v_cvt_pk_bf16_f32 v39, v6, v7
	ds_read_b128 v[6:9], v128 offset:24960
	v_lshl_add_u64 v[40:41], v[42:43], 0, v[86:87]
	s_waitcnt vmcnt(10) lgkmcnt(1)
	v_pk_fma_f32 v[2:3], v[64:65], v[2:3], v[10:11]
	s_nop 0
	v_cvt_pk_bf16_f32 v10, v2, v3
	v_pk_fma_f32 v[2:3], v[66:67], v[4:5], v[12:13]
	v_lshl_add_u64 v[12:13], v[42:43], 0, v[88:89]
	v_cvt_pk_bf16_f32 v11, v2, v3
	s_waitcnt vmcnt(8) lgkmcnt(0)
; DI unsigned pk_bf16(float lo, float hi) { f32x2v v = {lo, hi}; bf16x2v b = __builtin_convertvector(v, bf16x2v); return __builtin_bit_cast(unsigned, b); }
; DI void lds_sync() { wait_lgkm0(); bar_(); }
; DI void phase6(const Params& p, char* smem) {
;     ...
; #pragma unroll
;       for (int hb = 0; hb < 2; ++hb) {
;         float4 xv[8];
; #pragma unroll
;         for (int i = 0; i < 8; ++i) {
;           const int row = r0 + 8 * (hb * 8 + i);
;           xv[i] = *(const float4*)(p.x + obase + (size_t)((row >> 5) * 64 + (row & 31)) * DM);
;         }
; #pragma unroll
;         for (int i = 0; i < 8; ++i) {
;           const int row = r0 + 8 * (hb * 8 + i);
;           const float4 a = *(const float4*)(smem + row * 1040 + ch * 16);
;           uint2 ob; ob.x = pk_bf16(xv[i].x + g.x * a.x, xv[i].y + g.y * a.y); ob.y = pk_bf16(xv[i].z + g.z * a.z, xv[i].w + g.w * a.w);
;           *(uint2*)(p.x1b + obase + (size_t)((row >> 5) * 64 + (row & 31)) * DM) = ob;
;         }
;       }
;       lds_sync();
;     }
	v_pk_fma_f32 v[2:3], v[64:65], v[6:7], v[14:15]
	v_pk_fma_f32 v[6:7], v[66:67], v[8:9], v[16:17]
	v_cvt_pk_bf16_f32 v14, v2, v3
	ds_read_b128 v[2:5], v128 offset:33280
	v_cvt_pk_bf16_f32 v15, v6, v7
	ds_read_b128 v[6:9], v128 offset:41600
	v_lshl_add_u64 v[16:17], v[42:43], 0, v[90:91]
	s_waitcnt vmcnt(6) lgkmcnt(1)
	v_pk_fma_f32 v[2:3], v[64:65], v[2:3], v[18:19]
	s_nop 0
	v_cvt_pk_bf16_f32 v18, v2, v3
	v_pk_fma_f32 v[2:3], v[66:67], v[4:5], v[20:21]
	v_lshl_add_u64 v[20:21], v[42:43], 0, v[92:93]
	v_cvt_pk_bf16_f32 v19, v2, v3
	s_waitcnt vmcnt(4) lgkmcnt(0)
	v_pk_fma_f32 v[2:3], v[64:65], v[6:7], v[22:23]
	v_pk_fma_f32 v[6:7], v[66:67], v[8:9], v[24:25]
	v_cvt_pk_bf16_f32 v22, v2, v3
	ds_read_b128 v[2:5], v128 offset:49920
	v_cvt_pk_bf16_f32 v23, v6, v7
	ds_read_b128 v[6:9], v128 offset:58240
	v_lshl_add_u64 v[24:25], v[42:43], 0, v[94:95]
	s_waitcnt vmcnt(2) lgkmcnt(1)
	v_pk_fma_f32 v[2:3], v[64:65], v[2:3], v[26:27]
	v_pk_fma_f32 v[4:5], v[66:67], v[4:5], v[28:29]
	v_cvt_pk_bf16_f32 v2, v2, v3
	v_cvt_pk_bf16_f32 v3, v4, v5
	v_lshl_add_u64 v[4:5], v[42:43], 0, v[96:97]
	s_waitcnt vmcnt(0) lgkmcnt(0)
	v_pk_fma_f32 v[6:7], v[64:65], v[6:7], v[30:31]
	global_store_dwordx2 v[36:37], v[34:35], off
	global_store_dwordx2 v[40:41], v[38:39], off
	global_store_dwordx2 v[12:13], v[10:11], off
	global_store_dwordx2 v[16:17], v[14:15], off
	global_store_dwordx2 v[20:21], v[18:19], off
	global_store_dwordx2 v[24:25], v[22:23], off
	global_store_dwordx2 v[4:5], v[2:3], off
	v_pk_fma_f32 v[2:3], v[66:67], v[8:9], v[32:33]
	v_cvt_pk_bf16_f32 v6, v6, v7
	v_cvt_pk_bf16_f32 v7, v2, v3
	v_lshl_add_u64 v[2:3], v[42:43], 0, v[98:99]
	global_store_dwordx2 v[2:3], v[6:7], off
	v_lshl_add_u64 v[2:3], v[0:1], 0, v[100:101]
	v_mov_b64_e32 v[2:3], v[192:193]
	v_mov_b64_e32 v[4:5], v[194:195]
	v_lshl_add_u64 v[6:7], v[0:1], 0, v[102:103]
	v_mov_b64_e32 v[6:7], v[196:197]
	v_mov_b64_e32 v[8:9], v[198:199]
	v_lshl_add_u64 v[10:11], v[0:1], 0, v[104:105]
	v_mov_b64_e32 v[10:11], v[204:205]
	v_mov_b64_e32 v[12:13], v[206:207]
	v_lshl_add_u64 v[14:15], v[0:1], 0, v[106:107]
	v_mov_b64_e32 v[14:15], v[208:209]
	v_mov_b64_e32 v[16:17], v[210:211]
	v_lshl_add_u64 v[18:19], v[0:1], 0, v[108:109]
	v_mov_b64_e32 v[18:19], v[212:213]
	v_mov_b64_e32 v[20:21], v[214:215]
	v_lshl_add_u64 v[22:23], v[0:1], 0, v[110:111]
	v_mov_b64_e32 v[22:23], v[216:217]
	v_mov_b64_e32 v[24:25], v[218:219]
	v_lshl_add_u64 v[26:27], v[0:1], 0, v[112:113]
	v_mov_b64_e32 v[26:27], v[222:223]
	v_mov_b64_e32 v[28:29], v[224:225]
	v_lshl_add_u64 v[0:1], v[0:1], 0, v[114:115]
	v_mov_b64_e32 v[30:31], v[226:227]
	v_mov_b64_e32 v[32:33], v[228:229]
	ds_read_b128 v[34:37], v129
	ds_read_b128 v[38:41], v137 offset:58240
	s_waitcnt lgkmcnt(1)
	v_pk_fma_f32 v[0:1], v[64:65], v[34:35], v[2:3]
	s_nop 0
	v_cvt_pk_bf16_f32 v34, v0, v1
	v_pk_fma_f32 v[0:1], v[66:67], v[36:37], v[4:5]
	s_waitcnt lgkmcnt(0)
	v_pk_fma_f32 v[4:5], v[66:67], v[40:41], v[8:9]
	v_cvt_pk_bf16_f32 v35, v0, v1
	v_pk_fma_f32 v[0:1], v[64:65], v[38:39], v[6:7]
	v_cvt_pk_bf16_f32 v39, v4, v5
	v_cvt_pk_bf16_f32 v38, v0, v1
	ds_read_b128 v[0:3], v186 offset:58240
	ds_read_b128 v[4:7], v187 offset:58240
	v_lshl_add_u64 v[36:37], v[42:43], 0, v[116:117]
	v_lshl_add_u64 v[8:9], v[42:43], 0, v[118:119]
	s_waitcnt lgkmcnt(1)
	v_pk_fma_f32 v[0:1], v[64:65], v[0:1], v[10:11]
	s_nop 0
	v_cvt_pk_bf16_f32 v10, v0, v1
	v_pk_fma_f32 v[0:1], v[66:67], v[2:3], v[12:13]
	v_lshl_add_u64 v[12:13], v[42:43], 0, v[120:121]
	v_cvt_pk_bf16_f32 v11, v0, v1
	s_waitcnt lgkmcnt(0)
	v_pk_fma_f32 v[0:1], v[64:65], v[4:5], v[14:15]
	v_pk_fma_f32 v[4:5], v[66:67], v[6:7], v[16:17]
	v_cvt_pk_bf16_f32 v14, v0, v1
	ds_read_b128 v[0:3], v188 offset:58240
	v_cvt_pk_bf16_f32 v15, v4, v5
	ds_read_b128 v[4:7], v189 offset:58240
	v_lshl_add_u64 v[16:17], v[42:43], 0, v[122:123]
	s_waitcnt lgkmcnt(1)
	v_pk_fma_f32 v[0:1], v[64:65], v[0:1], v[18:19]
	s_nop 0
	v_cvt_pk_bf16_f32 v18, v0, v1
	v_pk_fma_f32 v[0:1], v[66:67], v[2:3], v[20:21]
	v_lshl_add_u64 v[20:21], v[42:43], 0, v[124:125]
	v_cvt_pk_bf16_f32 v19, v0, v1
	s_waitcnt lgkmcnt(0)
	v_pk_fma_f32 v[0:1], v[64:65], v[4:5], v[22:23]
	v_pk_fma_f32 v[4:5], v[66:67], v[6:7], v[24:25]
	v_cvt_pk_bf16_f32 v22, v0, v1
	ds_read_b128 v[0:3], v190 offset:58240
	v_cvt_pk_bf16_f32 v23, v4, v5
	ds_read_b128 v[4:7], v191 offset:49920
	v_lshl_add_u64 v[24:25], v[42:43], 0, v[126:127]
	s_waitcnt lgkmcnt(1)
	v_pk_fma_f32 v[0:1], v[64:65], v[0:1], v[26:27]
	v_pk_fma_f32 v[2:3], v[66:67], v[2:3], v[28:29]
	v_cvt_pk_bf16_f32 v0, v0, v1
	v_cvt_pk_bf16_f32 v1, v2, v3
	v_lshl_add_u64 v[2:3], v[42:43], 0, v[130:131]
	s_waitcnt lgkmcnt(0)
	v_pk_fma_f32 v[4:5], v[64:65], v[4:5], v[30:31]
	global_store_dwordx2 v[36:37], v[34:35], off
	global_store_dwordx2 v[8:9], v[38:39], off
	global_store_dwordx2 v[12:13], v[10:11], off
	global_store_dwordx2 v[16:17], v[14:15], off
	global_store_dwordx2 v[20:21], v[18:19], off
	global_store_dwordx2 v[24:25], v[22:23], off
	global_store_dwordx2 v[2:3], v[0:1], off
	v_pk_fma_f32 v[0:1], v[66:67], v[6:7], v[32:33]
	v_cvt_pk_bf16_f32 v4, v4, v5
	v_cvt_pk_bf16_f32 v5, v0, v1
	v_lshl_add_u64 v[0:1], v[42:43], 0, v[132:133]
	global_store_dwordx2 v[0:1], v[4:5], off
	s_waitcnt lgkmcnt(0)
	s_barrier
	s_cbranch_scc0 .LBB0_929
